# gate/up epilogue: the 8 per-row rinv loads hoisted to the epilogue start (one wait instead of a load+store round trip per row group)
# speedup vs baseline: 1.0103x; 1.0103x over previous
; __device__ __forceinline__ u32x4 pack8(f32x4 a, f32x4 b) { u32x4 w; w.x = pkbf(a[0], a[1]); w.y = pkbf(a[2], a[3]); w.z = pkbf(b[0], b[1]); w.w = pkbf(b[2], b[3]); return w; }
;     __device__ __forceinline__ void operator()(const f32x4 (&acc)[2][2][4][2], const Unit& u, int wr, int wc, int fr, int fq) const {
;         const int row0 = u.pm * BM + wr * 64 + fr, col0 = u.pn * HALF + wc * 32 + 8 * fq;
; #pragma unroll
;         for (int ai = 0; ai < 2; ++ai)
; #pragma unroll
;             for (int m = 0; m < 4; ++m) { const int row = row0 + ai * HALF + m * 16; const float rs = rinv[row]; f32x4 h[2];
; #pragma unroll
;                 for (int n = 0; n < 2; ++n) { const f32x4 g = acc[ai][0][m][n] * rs, up = acc[ai][1][m][n] * rs;
; #pragma unroll
;                     for (int e = 0; e < 4; ++e) { const float ex = __builtin_amdgcn_exp2f(g[e] * -1.4426950408889634f); h[n][e] = g[e] * __builtin_amdgcn_rcpf(1.0f + ex) * up[e]; } }
;                 *(u32x4*)(H + (size_t)row * ldc + col0) = pack8(h[0], h[1]); }
.LBB0_547:
	v_lshl_add_u32 v138, s78, 8, v145
	v_ashrrev_i32_e32 v139, 31, v138
	v_lshl_add_u64 v[140:141], v[138:139], 2, s[2:3]
	global_load_dword v154, v[140:141], off
	global_load_dword v156, v[140:141], off offset:64
	global_load_dword v158, v[140:141], off offset:128
	global_load_dword v160, v[140:141], off offset:192
	global_load_dword v162, v[140:141], off offset:512
	global_load_dword v164, v[140:141], off offset:576
	global_load_dword v166, v[140:141], off offset:640
	global_load_dword v168, v[140:141], off offset:704
	v_mov_b32_e32 v150, v120
	v_mov_b32_e32 v151, v124
	v_mov_b32_e32 v124, v121
	v_lshl_or_b32 v142, s44, 7, v147
	v_ashrrev_i32_e32 v143, 31, v142
	s_mov_b64 s[78:79], -1
	s_andn2_b64 vcc, exec, s[38:39]
	s_waitcnt vmcnt(0) lgkmcnt(0)
	v_pk_mul_f32 v[150:151], v[150:151], v[154:155] op_sel_hi:[1,0]
	s_nop 0
	v_mul_f32_e32 v120, 0xbfb8aa3b, v151
	v_exp_f32_e32 v120, v120
	s_nop 0
	v_add_f32_e32 v120, 1.0, v120
	v_rcp_f32_e32 v120, v120
	s_nop 0
	v_mul_f32_e32 v120, v151, v120
	v_mul_f32_e32 v139, v150, v120
	v_pk_mul_f32 v[120:121], v[124:125], v[154:155] op_sel_hi:[1,0]
	s_nop 0
	v_mul_f32_e32 v124, 0xbfb8aa3b, v121
	v_exp_f32_e32 v124, v124
	s_nop 0
	v_add_f32_e32 v124, 1.0, v124
	v_rcp_f32_e32 v124, v124
	s_nop 0
	v_mul_f32_e32 v121, v121, v124
	v_mul_f32_e32 v124, v120, v121
	v_mov_b32_e32 v120, v122
	v_mov_b32_e32 v121, v126
	v_pk_mul_f32 v[120:121], v[120:121], v[154:155] op_sel_hi:[1,0]
	v_mov_b32_e32 v126, v123
	v_mul_f32_e32 v122, 0xbfb8aa3b, v121
	v_exp_f32_e32 v122, v122
	s_nop 0
	v_add_f32_e32 v122, 1.0, v122
	v_rcp_f32_e32 v122, v122
	s_nop 0
	v_mul_f32_e32 v121, v121, v122
	v_mul_f32_e32 v122, v120, v121
	v_pk_mul_f32 v[120:121], v[126:127], v[154:155] op_sel_hi:[1,0]
	s_nop 0
	v_mul_f32_e32 v123, 0xbfb8aa3b, v121
	v_exp_f32_e32 v123, v123
	s_nop 0
	v_add_f32_e32 v123, 1.0, v123
	v_rcp_f32_e32 v123, v123
	s_nop 0
	v_mul_f32_e32 v121, v121, v123
	v_mul_f32_e32 v123, v120, v121
	v_mov_b32_e32 v120, v112
	v_mov_b32_e32 v121, v116
	v_pk_mul_f32 v[120:121], v[120:121], v[154:155] op_sel_hi:[1,0]
	v_mov_b32_e32 v116, v113
	v_mul_f32_e32 v112, 0xbfb8aa3b, v121
	v_exp_f32_e32 v112, v112
	s_nop 0
	v_add_f32_e32 v112, 1.0, v112
	v_rcp_f32_e32 v112, v112
	s_nop 0
	v_mul_f32_e32 v112, v121, v112
	v_mul_f32_e32 v120, v120, v112
	v_pk_mul_f32 v[112:113], v[116:117], v[154:155] op_sel_hi:[1,0]
	v_cvt_pk_bf16_f32 v117, v122, v123
	s_nop 0
	v_mul_f32_e32 v116, 0xbfb8aa3b, v113
	v_exp_f32_e32 v116, v116
	s_nop 0
	v_add_f32_e32 v116, 1.0, v116
	v_rcp_f32_e32 v116, v116
	s_nop 0
	v_mul_f32_e32 v113, v113, v116
	v_mul_f32_e32 v121, v112, v113
	v_mov_b32_e32 v112, v114
	v_mov_b32_e32 v113, v118
	v_pk_mul_f32 v[112:113], v[112:113], v[154:155] op_sel_hi:[1,0]
	v_mov_b32_e32 v118, v115
	v_mul_f32_e32 v114, 0xbfb8aa3b, v113
	v_exp_f32_e32 v114, v114
	v_cvt_pk_bf16_f32 v116, v139, v124
	s_nop 0
	v_add_f32_e32 v114, 1.0, v114
	v_rcp_f32_e32 v114, v114
	s_nop 0
	v_mul_f32_e32 v113, v113, v114
	v_mul_f32_e32 v114, v112, v113
	v_pk_mul_f32 v[112:113], v[118:119], v[154:155] op_sel_hi:[1,0]
	v_cvt_pk_bf16_f32 v118, v120, v121
	s_nop 0
	v_mul_f32_e32 v115, 0xbfb8aa3b, v113
	v_exp_f32_e32 v115, v115
	s_nop 0
	v_add_f32_e32 v115, 1.0, v115
	v_rcp_f32_e32 v115, v115
	s_nop 0
	v_mul_f32_e32 v113, v113, v115
	v_mul_f32_e32 v112, v112, v113
	v_cvt_pk_bf16_f32 v119, v114, v112
	v_mov_b64_e32 v[112:113], s[40:41]
	v_mad_i64_i32 v[120:121], s[10:11], v138, s47, v[112:113]
	v_lshlrev_b64 v[114:115], 1, v[142:143]
	v_lshl_add_u64 v[120:121], v[120:121], 0, v[114:115]
	flat_store_dwordx4 v[120:121], v[116:119]
	v_mov_b32_e32 v120, v104
	v_mov_b32_e32 v121, v108
	v_or_b32_e32 v116, 16, v138
	v_ashrrev_i32_e32 v117, 31, v116
	v_lshl_add_u64 v[118:119], v[116:117], 2, s[2:3]
	s_nop 0
	v_mov_b32_e32 v108, v105
	s_nop 0
	v_pk_mul_f32 v[120:121], v[120:121], v[156:157] op_sel_hi:[1,0]
	s_nop 0
	v_mul_f32_e32 v104, 0xbfb8aa3b, v121
	v_exp_f32_e32 v104, v104
	s_nop 0
	v_add_f32_e32 v104, 1.0, v104
	v_rcp_f32_e32 v104, v104
	s_nop 0
	v_mul_f32_e32 v104, v121, v104
	v_mul_f32_e32 v117, v120, v104
	v_pk_mul_f32 v[104:105], v[108:109], v[156:157] op_sel_hi:[1,0]
	s_nop 0
	v_mul_f32_e32 v108, 0xbfb8aa3b, v105
	v_exp_f32_e32 v108, v108
	s_nop 0
	v_add_f32_e32 v108, 1.0, v108
	v_rcp_f32_e32 v108, v108
	s_nop 0
	v_mul_f32_e32 v105, v105, v108
	v_mul_f32_e32 v108, v104, v105
	v_mov_b32_e32 v104, v106
	v_mov_b32_e32 v105, v110
	v_pk_mul_f32 v[104:105], v[104:105], v[156:157] op_sel_hi:[1,0]
	v_mov_b32_e32 v110, v107
	v_mul_f32_e32 v106, 0xbfb8aa3b, v105
	v_exp_f32_e32 v106, v106
	s_nop 0
	v_add_f32_e32 v106, 1.0, v106
	v_rcp_f32_e32 v106, v106
	s_nop 0
	v_mul_f32_e32 v105, v105, v106
	v_mul_f32_e32 v106, v104, v105
	v_pk_mul_f32 v[104:105], v[110:111], v[156:157] op_sel_hi:[1,0]
	s_nop 0
	v_mul_f32_e32 v107, 0xbfb8aa3b, v105
	v_exp_f32_e32 v107, v107
	s_nop 0
	v_add_f32_e32 v107, 1.0, v107
	v_rcp_f32_e32 v107, v107
	s_nop 0
	v_mul_f32_e32 v105, v105, v107
	v_mul_f32_e32 v107, v104, v105
	v_mov_b32_e32 v104, v96
	v_mov_b32_e32 v105, v100
	v_pk_mul_f32 v[104:105], v[104:105], v[156:157] op_sel_hi:[1,0]
	v_mov_b32_e32 v100, v97
	v_mul_f32_e32 v96, 0xbfb8aa3b, v105
	v_exp_f32_e32 v96, v96
	s_nop 0
	v_add_f32_e32 v96, 1.0, v96
	v_rcp_f32_e32 v96, v96
	s_nop 0
	v_mul_f32_e32 v96, v105, v96
	v_mul_f32_e32 v104, v104, v96
	v_pk_mul_f32 v[96:97], v[100:101], v[156:157] op_sel_hi:[1,0]
	s_nop 0
	v_mul_f32_e32 v100, 0xbfb8aa3b, v97
	v_exp_f32_e32 v100, v100
	s_nop 0
	v_add_f32_e32 v100, 1.0, v100
	v_rcp_f32_e32 v100, v100
	s_nop 0
	v_mul_f32_e32 v97, v97, v100
	v_mul_f32_e32 v100, v96, v97
	v_mov_b32_e32 v96, v98
	v_mov_b32_e32 v97, v102
	v_pk_mul_f32 v[96:97], v[96:97], v[156:157] op_sel_hi:[1,0]
; __device__ __forceinline__ u32x4 pack8(f32x4 a, f32x4 b) { u32x4 w; w.x = pkbf(a[0], a[1]); w.y = pkbf(a[2], a[3]); w.z = pkbf(b[0], b[1]); w.w = pkbf(b[2], b[3]); return w; }
;     __device__ __forceinline__ void operator()(const f32x4 (&acc)[2][2][4][2], const Unit& u, int wr, int wc, int fr, int fq) const {
;     ...
;             for (int m = 0; m < 4; ++m) { const int row = row0 + ai * HALF + m * 16; const float rs = rinv[row]; f32x4 h[2];
; #pragma unroll
;                 for (int n = 0; n < 2; ++n) { const f32x4 g = acc[ai][0][m][n] * rs, up = acc[ai][1][m][n] * rs;
; #pragma unroll
;                     for (int e = 0; e < 4; ++e) { const float ex = __builtin_amdgcn_exp2f(g[e] * -1.4426950408889634f); h[n][e] = g[e] * __builtin_amdgcn_rcpf(1.0f + ex) * up[e]; } }
;                 *(u32x4*)(H + (size_t)row * ldc + col0) = pack8(h[0], h[1]); }
	v_mov_b32_e32 v102, v99
	v_mul_f32_e32 v98, 0xbfb8aa3b, v97
	v_exp_f32_e32 v98, v98
	s_nop 0
	v_add_f32_e32 v98, 1.0, v98
	v_rcp_f32_e32 v98, v98
	s_nop 0
	v_mul_f32_e32 v97, v97, v98
	v_mul_f32_e32 v101, v96, v97
	v_pk_mul_f32 v[96:97], v[102:103], v[156:157] op_sel_hi:[1,0]
	s_nop 0
	v_mul_f32_e32 v98, 0xbfb8aa3b, v97
	v_exp_f32_e32 v98, v98
	s_nop 0
	v_add_f32_e32 v98, 1.0, v98
	v_rcp_f32_e32 v98, v98
	s_nop 0
	v_mul_f32_e32 v97, v97, v98
	v_mul_f32_e32 v99, v96, v97
	v_cvt_pk_bf16_f32 v98, v104, v100
	v_cvt_pk_bf16_f32 v99, v101, v99
	v_mad_i64_i32 v[100:101], s[10:11], v116, s47, v[112:113]
	v_cvt_pk_bf16_f32 v96, v117, v108
	v_lshl_add_u64 v[100:101], v[100:101], 0, v[114:115]
	v_cvt_pk_bf16_f32 v97, v106, v107
	flat_store_dwordx4 v[100:101], v[96:99]
	v_mov_b32_e32 v100, v88
	v_mov_b32_e32 v101, v92
	v_or_b32_e32 v96, 32, v138
	v_ashrrev_i32_e32 v97, 31, v96
	v_lshl_add_u64 v[98:99], v[96:97], 2, s[2:3]
	s_nop 0
	v_mov_b32_e32 v92, v89
	s_nop 0
	v_pk_mul_f32 v[100:101], v[100:101], v[158:159] op_sel_hi:[1,0]
	s_nop 0
	v_mul_f32_e32 v88, 0xbfb8aa3b, v101
	v_exp_f32_e32 v88, v88
	s_nop 0
	v_add_f32_e32 v88, 1.0, v88
	v_rcp_f32_e32 v88, v88
	s_nop 0
	v_mul_f32_e32 v88, v101, v88
	v_mul_f32_e32 v97, v100, v88
	v_pk_mul_f32 v[88:89], v[92:93], v[158:159] op_sel_hi:[1,0]
	s_nop 0
	v_mul_f32_e32 v92, 0xbfb8aa3b, v89
	v_exp_f32_e32 v92, v92
	s_nop 0
	v_add_f32_e32 v92, 1.0, v92
	v_rcp_f32_e32 v92, v92
	s_nop 0
	v_mul_f32_e32 v89, v89, v92
	v_mul_f32_e32 v92, v88, v89
	v_mov_b32_e32 v88, v90
	v_mov_b32_e32 v89, v94
	v_pk_mul_f32 v[88:89], v[88:89], v[158:159] op_sel_hi:[1,0]
	v_mov_b32_e32 v94, v91
	v_mul_f32_e32 v90, 0xbfb8aa3b, v89
	v_exp_f32_e32 v90, v90
	s_nop 0
	v_add_f32_e32 v90, 1.0, v90
	v_rcp_f32_e32 v90, v90
	s_nop 0
	v_mul_f32_e32 v89, v89, v90
	v_mul_f32_e32 v90, v88, v89
	v_pk_mul_f32 v[88:89], v[94:95], v[158:159] op_sel_hi:[1,0]
	s_nop 0
	v_mul_f32_e32 v91, 0xbfb8aa3b, v89
	v_exp_f32_e32 v91, v91
	s_nop 0
	v_add_f32_e32 v91, 1.0, v91
	v_rcp_f32_e32 v91, v91
	s_nop 0
	v_mul_f32_e32 v89, v89, v91
	v_mul_f32_e32 v91, v88, v89
	v_mov_b32_e32 v88, v80
	v_mov_b32_e32 v89, v84
	v_pk_mul_f32 v[88:89], v[88:89], v[158:159] op_sel_hi:[1,0]
	v_mov_b32_e32 v84, v81
	v_mul_f32_e32 v80, 0xbfb8aa3b, v89
	v_exp_f32_e32 v80, v80
	s_nop 0
	v_add_f32_e32 v80, 1.0, v80
	v_rcp_f32_e32 v80, v80
	s_nop 0
	v_mul_f32_e32 v80, v89, v80
	v_mul_f32_e32 v88, v88, v80
	v_pk_mul_f32 v[80:81], v[84:85], v[158:159] op_sel_hi:[1,0]
	s_nop 0
	v_mul_f32_e32 v84, 0xbfb8aa3b, v81
	v_exp_f32_e32 v84, v84
	s_nop 0
	v_add_f32_e32 v84, 1.0, v84
	v_rcp_f32_e32 v84, v84
	s_nop 0
	v_mul_f32_e32 v81, v81, v84
	v_mul_f32_e32 v84, v80, v81
	v_mov_b32_e32 v80, v82
	v_mov_b32_e32 v81, v86
	v_pk_mul_f32 v[80:81], v[80:81], v[158:159] op_sel_hi:[1,0]
	v_mov_b32_e32 v86, v83
	v_mul_f32_e32 v82, 0xbfb8aa3b, v81
	v_exp_f32_e32 v82, v82
	s_nop 0
	v_add_f32_e32 v82, 1.0, v82
	v_rcp_f32_e32 v82, v82
	s_nop 0
	v_mul_f32_e32 v81, v81, v82
	v_mul_f32_e32 v85, v80, v81
	v_pk_mul_f32 v[80:81], v[86:87], v[158:159] op_sel_hi:[1,0]
	s_nop 0
	v_mul_f32_e32 v82, 0xbfb8aa3b, v81
	v_exp_f32_e32 v82, v82
	s_nop 0
	v_add_f32_e32 v82, 1.0, v82
	v_rcp_f32_e32 v82, v82
	s_nop 0
	v_mul_f32_e32 v81, v81, v82
	v_mul_f32_e32 v83, v80, v81
	v_cvt_pk_bf16_f32 v82, v88, v84
	v_cvt_pk_bf16_f32 v83, v85, v83
	v_mad_i64_i32 v[84:85], s[10:11], v96, s47, v[112:113]
	v_cvt_pk_bf16_f32 v80, v97, v92
	v_lshl_add_u64 v[84:85], v[84:85], 0, v[114:115]
	v_cvt_pk_bf16_f32 v81, v90, v91
	flat_store_dwordx4 v[84:85], v[80:83]
	v_mov_b32_e32 v84, v72
	v_mov_b32_e32 v85, v76
	v_or_b32_e32 v80, 48, v138
	v_ashrrev_i32_e32 v81, 31, v80
	v_lshl_add_u64 v[82:83], v[80:81], 2, s[2:3]
	s_nop 0
	v_mov_b32_e32 v76, v73
	s_nop 0
	v_pk_mul_f32 v[84:85], v[84:85], v[160:161] op_sel_hi:[1,0]
	s_nop 0
	v_mul_f32_e32 v72, 0xbfb8aa3b, v85
	v_exp_f32_e32 v72, v72
	s_nop 0
	v_add_f32_e32 v72, 1.0, v72
	v_rcp_f32_e32 v72, v72
	s_nop 0
	v_mul_f32_e32 v72, v85, v72
	v_mul_f32_e32 v81, v84, v72
	v_pk_mul_f32 v[72:73], v[76:77], v[160:161] op_sel_hi:[1,0]
	s_nop 0
	v_mul_f32_e32 v76, 0xbfb8aa3b, v73
	v_exp_f32_e32 v76, v76
	s_nop 0
	v_add_f32_e32 v76, 1.0, v76
	v_rcp_f32_e32 v76, v76
	s_nop 0
	v_mul_f32_e32 v73, v73, v76
	v_mul_f32_e32 v76, v72, v73
	v_mov_b32_e32 v72, v74
	v_mov_b32_e32 v73, v78
	v_pk_mul_f32 v[72:73], v[72:73], v[160:161] op_sel_hi:[1,0]
	v_mov_b32_e32 v78, v75
	v_mul_f32_e32 v74, 0xbfb8aa3b, v73
	v_exp_f32_e32 v74, v74
	s_nop 0
	v_add_f32_e32 v74, 1.0, v74
	v_rcp_f32_e32 v74, v74
	s_nop 0
	v_mul_f32_e32 v73, v73, v74
	v_mul_f32_e32 v74, v72, v73
	v_pk_mul_f32 v[72:73], v[78:79], v[160:161] op_sel_hi:[1,0]
	s_nop 0
	v_mul_f32_e32 v75, 0xbfb8aa3b, v73
	v_exp_f32_e32 v75, v75
	s_nop 0
	v_add_f32_e32 v75, 1.0, v75
	v_rcp_f32_e32 v75, v75
	s_nop 0
	v_mul_f32_e32 v73, v73, v75
	v_mul_f32_e32 v75, v72, v73
	v_mov_b32_e32 v72, v64
	v_mov_b32_e32 v73, v68
	v_pk_mul_f32 v[72:73], v[72:73], v[160:161] op_sel_hi:[1,0]
	v_mov_b32_e32 v68, v65
	v_mul_f32_e32 v64, 0xbfb8aa3b, v73
	v_exp_f32_e32 v64, v64
	s_nop 0
	v_add_f32_e32 v64, 1.0, v64
	v_rcp_f32_e32 v64, v64
	s_nop 0
	v_mul_f32_e32 v64, v73, v64
	v_mul_f32_e32 v72, v72, v64
	v_pk_mul_f32 v[64:65], v[68:69], v[160:161] op_sel_hi:[1,0]
	s_nop 0
	v_mul_f32_e32 v68, 0xbfb8aa3b, v65
	v_exp_f32_e32 v68, v68
	s_nop 0
	v_add_f32_e32 v68, 1.0, v68
	v_rcp_f32_e32 v68, v68
	s_nop 0
	v_mul_f32_e32 v65, v65, v68
	v_mul_f32_e32 v68, v64, v65
	v_mov_b32_e32 v64, v66
	v_mov_b32_e32 v65, v70
	v_pk_mul_f32 v[64:65], v[64:65], v[160:161] op_sel_hi:[1,0]
	v_mov_b32_e32 v70, v67
	v_mul_f32_e32 v66, 0xbfb8aa3b, v65
	v_exp_f32_e32 v66, v66
	s_nop 0
	v_add_f32_e32 v66, 1.0, v66
	v_rcp_f32_e32 v66, v66
; __device__ __forceinline__ u32x4 pack8(f32x4 a, f32x4 b) { u32x4 w; w.x = pkbf(a[0], a[1]); w.y = pkbf(a[2], a[3]); w.z = pkbf(b[0], b[1]); w.w = pkbf(b[2], b[3]); return w; }
;     __device__ __forceinline__ void operator()(const f32x4 (&acc)[2][2][4][2], const Unit& u, int wr, int wc, int fr, int fq) const {
;     ...
;             for (int m = 0; m < 4; ++m) { const int row = row0 + ai * HALF + m * 16; const float rs = rinv[row]; f32x4 h[2];
; #pragma unroll
;                 for (int n = 0; n < 2; ++n) { const f32x4 g = acc[ai][0][m][n] * rs, up = acc[ai][1][m][n] * rs;
; #pragma unroll
;                     for (int e = 0; e < 4; ++e) { const float ex = __builtin_amdgcn_exp2f(g[e] * -1.4426950408889634f); h[n][e] = g[e] * __builtin_amdgcn_rcpf(1.0f + ex) * up[e]; } }
;                 *(u32x4*)(H + (size_t)row * ldc + col0) = pack8(h[0], h[1]); }
	s_nop 0
	v_mul_f32_e32 v65, v65, v66
	v_mul_f32_e32 v69, v64, v65
	v_pk_mul_f32 v[64:65], v[70:71], v[160:161] op_sel_hi:[1,0]
	s_nop 0
	v_mul_f32_e32 v66, 0xbfb8aa3b, v65
	v_exp_f32_e32 v66, v66
	s_nop 0
	v_add_f32_e32 v66, 1.0, v66
	v_rcp_f32_e32 v66, v66
	s_nop 0
	v_mul_f32_e32 v65, v65, v66
	v_mul_f32_e32 v67, v64, v65
	v_cvt_pk_bf16_f32 v66, v72, v68
	v_cvt_pk_bf16_f32 v67, v69, v67
	v_mad_i64_i32 v[68:69], s[10:11], v80, s47, v[112:113]
	v_lshl_add_u64 v[68:69], v[68:69], 0, v[114:115]
	v_cvt_pk_bf16_f32 v64, v81, v76
	v_cvt_pk_bf16_f32 v65, v74, v75
	flat_store_dwordx4 v[68:69], v[64:67]
	s_nop 0
	s_nop 0
	v_add_u32_e32 v65, 0x80, v138
	v_mov_b32_e32 v66, v56
	v_mov_b32_e32 v67, v60
	v_mov_b32_e32 v60, v57
	s_nop 0
	v_pk_mul_f32 v[66:67], v[66:67], v[162:163] op_sel_hi:[1,0]
	s_nop 0
	v_mul_f32_e32 v56, 0xbfb8aa3b, v67
	v_exp_f32_e32 v56, v56
	s_nop 0
	v_add_f32_e32 v56, 1.0, v56
	v_rcp_f32_e32 v56, v56
	s_nop 0
	v_mul_f32_e32 v56, v67, v56
	v_mul_f32_e32 v66, v66, v56
	v_pk_mul_f32 v[56:57], v[60:61], v[162:163] op_sel_hi:[1,0]
	s_nop 0
	v_mul_f32_e32 v60, 0xbfb8aa3b, v57
	v_exp_f32_e32 v60, v60
	s_nop 0
	v_add_f32_e32 v60, 1.0, v60
	v_rcp_f32_e32 v60, v60
	s_nop 0
	v_mul_f32_e32 v57, v57, v60
	v_mul_f32_e32 v60, v56, v57
	v_mov_b32_e32 v56, v58
	v_mov_b32_e32 v57, v62
	v_pk_mul_f32 v[56:57], v[56:57], v[162:163] op_sel_hi:[1,0]
	v_mov_b32_e32 v62, v59
	v_mul_f32_e32 v58, 0xbfb8aa3b, v57
	v_exp_f32_e32 v58, v58
	s_nop 0
	v_add_f32_e32 v58, 1.0, v58
	v_rcp_f32_e32 v58, v58
	s_nop 0
	v_mul_f32_e32 v57, v57, v58
	v_mul_f32_e32 v58, v56, v57
	v_pk_mul_f32 v[56:57], v[62:63], v[162:163] op_sel_hi:[1,0]
	s_nop 0
	v_mul_f32_e32 v59, 0xbfb8aa3b, v57
	v_exp_f32_e32 v59, v59
	s_nop 0
	v_add_f32_e32 v59, 1.0, v59
	v_rcp_f32_e32 v59, v59
	s_nop 0
	v_mul_f32_e32 v57, v57, v59
	v_mul_f32_e32 v59, v56, v57
	v_mov_b32_e32 v56, v48
	v_mov_b32_e32 v57, v52
	v_pk_mul_f32 v[56:57], v[56:57], v[162:163] op_sel_hi:[1,0]
	v_mov_b32_e32 v52, v49
	v_mul_f32_e32 v48, 0xbfb8aa3b, v57
	v_exp_f32_e32 v48, v48
	s_nop 0
	v_add_f32_e32 v48, 1.0, v48
	v_rcp_f32_e32 v48, v48
	s_nop 0
	v_mul_f32_e32 v48, v57, v48
	v_mul_f32_e32 v56, v56, v48
	v_pk_mul_f32 v[48:49], v[52:53], v[162:163] op_sel_hi:[1,0]
	s_nop 0
	v_mul_f32_e32 v52, 0xbfb8aa3b, v49
	v_exp_f32_e32 v52, v52
	s_nop 0
	v_add_f32_e32 v52, 1.0, v52
	v_rcp_f32_e32 v52, v52
	s_nop 0
	v_mul_f32_e32 v49, v49, v52
	v_mul_f32_e32 v52, v48, v49
	v_mov_b32_e32 v48, v50
	v_mov_b32_e32 v49, v54
	v_pk_mul_f32 v[48:49], v[48:49], v[162:163] op_sel_hi:[1,0]
	v_mov_b32_e32 v54, v51
	v_mul_f32_e32 v50, 0xbfb8aa3b, v49
	v_exp_f32_e32 v50, v50
	s_nop 0
	v_add_f32_e32 v50, 1.0, v50
	v_rcp_f32_e32 v50, v50
	s_nop 0
	v_mul_f32_e32 v49, v49, v50
	v_mul_f32_e32 v53, v48, v49
	v_pk_mul_f32 v[48:49], v[54:55], v[162:163] op_sel_hi:[1,0]
	s_nop 0
	v_mul_f32_e32 v50, 0xbfb8aa3b, v49
	v_exp_f32_e32 v50, v50
	s_nop 0
	v_add_f32_e32 v50, 1.0, v50
	v_rcp_f32_e32 v50, v50
	s_nop 0
	v_mul_f32_e32 v49, v49, v50
	v_mul_f32_e32 v51, v48, v49
	v_cvt_pk_bf16_f32 v50, v56, v52
	v_cvt_pk_bf16_f32 v51, v53, v51
	v_mad_i64_i32 v[52:53], s[10:11], v65, s47, v[112:113]
	v_lshl_add_u64 v[52:53], v[52:53], 0, v[114:115]
	v_cvt_pk_bf16_f32 v48, v66, v60
	v_cvt_pk_bf16_f32 v49, v58, v59
	flat_store_dwordx4 v[52:53], v[48:51]
	s_nop 0
	s_nop 0
	v_add_u32_e32 v49, 0x90, v138
	v_mov_b32_e32 v50, v40
	v_mov_b32_e32 v51, v44
	v_mov_b32_e32 v44, v41
	s_nop 0
	v_pk_mul_f32 v[50:51], v[50:51], v[164:165] op_sel_hi:[1,0]
	s_nop 0
	v_mul_f32_e32 v40, 0xbfb8aa3b, v51
	v_exp_f32_e32 v40, v40
	s_nop 0
	v_add_f32_e32 v40, 1.0, v40
	v_rcp_f32_e32 v40, v40
	s_nop 0
	v_mul_f32_e32 v40, v51, v40
	v_mul_f32_e32 v50, v50, v40
	v_pk_mul_f32 v[40:41], v[44:45], v[164:165] op_sel_hi:[1,0]
	s_nop 0
	v_mul_f32_e32 v44, 0xbfb8aa3b, v41
	v_exp_f32_e32 v44, v44
	s_nop 0
	v_add_f32_e32 v44, 1.0, v44
	v_rcp_f32_e32 v44, v44
	s_nop 0
	v_mul_f32_e32 v41, v41, v44
	v_mul_f32_e32 v44, v40, v41
	v_mov_b32_e32 v40, v42
	v_mov_b32_e32 v41, v46
	v_pk_mul_f32 v[40:41], v[40:41], v[164:165] op_sel_hi:[1,0]
	v_mov_b32_e32 v46, v43
	v_mul_f32_e32 v42, 0xbfb8aa3b, v41
	v_exp_f32_e32 v42, v42
	s_nop 0
	v_add_f32_e32 v42, 1.0, v42
	v_rcp_f32_e32 v42, v42
	s_nop 0
	v_mul_f32_e32 v41, v41, v42
	v_mul_f32_e32 v42, v40, v41
	v_pk_mul_f32 v[40:41], v[46:47], v[164:165] op_sel_hi:[1,0]
	s_nop 0
	v_mul_f32_e32 v43, 0xbfb8aa3b, v41
	v_exp_f32_e32 v43, v43
	s_nop 0
	v_add_f32_e32 v43, 1.0, v43
	v_rcp_f32_e32 v43, v43
	s_nop 0
	v_mul_f32_e32 v41, v41, v43
	v_mul_f32_e32 v43, v40, v41
	v_mov_b32_e32 v40, v32
	v_mov_b32_e32 v41, v36
	v_pk_mul_f32 v[40:41], v[40:41], v[164:165] op_sel_hi:[1,0]
	v_mov_b32_e32 v36, v33
	v_mul_f32_e32 v32, 0xbfb8aa3b, v41
	v_exp_f32_e32 v32, v32
	s_nop 0
	v_add_f32_e32 v32, 1.0, v32
	v_rcp_f32_e32 v32, v32
	s_nop 0
	v_mul_f32_e32 v32, v41, v32
	v_mul_f32_e32 v40, v40, v32
	v_pk_mul_f32 v[32:33], v[36:37], v[164:165] op_sel_hi:[1,0]
	s_nop 0
	v_mul_f32_e32 v36, 0xbfb8aa3b, v33
	v_exp_f32_e32 v36, v36
	s_nop 0
	v_add_f32_e32 v36, 1.0, v36
	v_rcp_f32_e32 v36, v36
	s_nop 0
	v_mul_f32_e32 v33, v33, v36
	v_mul_f32_e32 v36, v32, v33
	v_mov_b32_e32 v32, v34
	v_mov_b32_e32 v33, v38
	v_pk_mul_f32 v[32:33], v[32:33], v[164:165] op_sel_hi:[1,0]
	v_mov_b32_e32 v38, v35
	v_mul_f32_e32 v34, 0xbfb8aa3b, v33
	v_exp_f32_e32 v34, v34
	s_nop 0
	v_add_f32_e32 v34, 1.0, v34
	v_rcp_f32_e32 v34, v34
	s_nop 0
	v_mul_f32_e32 v33, v33, v34
	v_mul_f32_e32 v37, v32, v33
	v_pk_mul_f32 v[32:33], v[38:39], v[164:165] op_sel_hi:[1,0]
	s_nop 0
	v_mul_f32_e32 v34, 0xbfb8aa3b, v33
	v_exp_f32_e32 v34, v34
	s_nop 0
	v_add_f32_e32 v34, 1.0, v34
	v_rcp_f32_e32 v34, v34
	s_nop 0
	v_mul_f32_e32 v33, v33, v34
; __device__ __forceinline__ u32x4 pack8(f32x4 a, f32x4 b) { u32x4 w; w.x = pkbf(a[0], a[1]); w.y = pkbf(a[2], a[3]); w.z = pkbf(b[0], b[1]); w.w = pkbf(b[2], b[3]); return w; }
;     __device__ __forceinline__ void operator()(const f32x4 (&acc)[2][2][4][2], const Unit& u, int wr, int wc, int fr, int fq) const {
;     ...
;             for (int m = 0; m < 4; ++m) { const int row = row0 + ai * HALF + m * 16; const float rs = rinv[row]; f32x4 h[2];
; #pragma unroll
;                 for (int n = 0; n < 2; ++n) { const f32x4 g = acc[ai][0][m][n] * rs, up = acc[ai][1][m][n] * rs;
; #pragma unroll
;                     for (int e = 0; e < 4; ++e) { const float ex = __builtin_amdgcn_exp2f(g[e] * -1.4426950408889634f); h[n][e] = g[e] * __builtin_amdgcn_rcpf(1.0f + ex) * up[e]; } }
;                 *(u32x4*)(H + (size_t)row * ldc + col0) = pack8(h[0], h[1]); }
	v_mul_f32_e32 v35, v32, v33
	v_cvt_pk_bf16_f32 v34, v40, v36
	v_cvt_pk_bf16_f32 v35, v37, v35
	v_mad_i64_i32 v[36:37], s[10:11], v49, s47, v[112:113]
	v_lshl_add_u64 v[36:37], v[36:37], 0, v[114:115]
	v_cvt_pk_bf16_f32 v32, v50, v44
	v_cvt_pk_bf16_f32 v33, v42, v43
	flat_store_dwordx4 v[36:37], v[32:35]
	s_nop 0
	s_nop 0
	v_add_u32_e32 v33, 0xa0, v138
	v_mov_b32_e32 v34, v24
	v_mov_b32_e32 v35, v28
	v_mov_b32_e32 v28, v25
	s_nop 0
	v_pk_mul_f32 v[34:35], v[34:35], v[166:167] op_sel_hi:[1,0]
	s_nop 0
	v_mul_f32_e32 v24, 0xbfb8aa3b, v35
	v_exp_f32_e32 v24, v24
	s_nop 0
	v_add_f32_e32 v24, 1.0, v24
	v_rcp_f32_e32 v24, v24
	s_nop 0
	v_mul_f32_e32 v24, v35, v24
	v_mul_f32_e32 v34, v34, v24
	v_pk_mul_f32 v[24:25], v[28:29], v[166:167] op_sel_hi:[1,0]
	s_nop 0
	v_mul_f32_e32 v28, 0xbfb8aa3b, v25
	v_exp_f32_e32 v28, v28
	s_nop 0
	v_add_f32_e32 v28, 1.0, v28
	v_rcp_f32_e32 v28, v28
	s_nop 0
	v_mul_f32_e32 v25, v25, v28
	v_mul_f32_e32 v28, v24, v25
	v_mov_b32_e32 v24, v26
	v_mov_b32_e32 v25, v30
	v_pk_mul_f32 v[24:25], v[24:25], v[166:167] op_sel_hi:[1,0]
	v_mov_b32_e32 v30, v27
	v_mul_f32_e32 v26, 0xbfb8aa3b, v25
	v_exp_f32_e32 v26, v26
	s_nop 0
	v_add_f32_e32 v26, 1.0, v26
	v_rcp_f32_e32 v26, v26
	s_nop 0
	v_mul_f32_e32 v25, v25, v26
	v_mul_f32_e32 v26, v24, v25
	v_pk_mul_f32 v[24:25], v[30:31], v[166:167] op_sel_hi:[1,0]
	s_nop 0
	v_mul_f32_e32 v27, 0xbfb8aa3b, v25
	v_exp_f32_e32 v27, v27
	s_nop 0
	v_add_f32_e32 v27, 1.0, v27
	v_rcp_f32_e32 v27, v27
	s_nop 0
	v_mul_f32_e32 v25, v25, v27
	v_mul_f32_e32 v27, v24, v25
	v_mov_b32_e32 v24, v16
	v_mov_b32_e32 v25, v20
	v_pk_mul_f32 v[24:25], v[24:25], v[166:167] op_sel_hi:[1,0]
	v_mov_b32_e32 v20, v17
	v_mul_f32_e32 v16, 0xbfb8aa3b, v25
	v_exp_f32_e32 v16, v16
	s_nop 0
	v_add_f32_e32 v16, 1.0, v16
	v_rcp_f32_e32 v16, v16
	s_nop 0
	v_mul_f32_e32 v16, v25, v16
	v_mul_f32_e32 v24, v24, v16
	v_pk_mul_f32 v[16:17], v[20:21], v[166:167] op_sel_hi:[1,0]
	s_nop 0
	v_mul_f32_e32 v20, 0xbfb8aa3b, v17
	v_exp_f32_e32 v20, v20
	s_nop 0
	v_add_f32_e32 v20, 1.0, v20
	v_rcp_f32_e32 v20, v20
	s_nop 0
	v_mul_f32_e32 v17, v17, v20
	v_mul_f32_e32 v20, v16, v17
	v_mov_b32_e32 v16, v18
	v_mov_b32_e32 v17, v22
	v_pk_mul_f32 v[16:17], v[16:17], v[166:167] op_sel_hi:[1,0]
	v_mov_b32_e32 v22, v19
	v_mul_f32_e32 v18, 0xbfb8aa3b, v17
	v_exp_f32_e32 v18, v18
	s_nop 0
	v_add_f32_e32 v18, 1.0, v18
	v_rcp_f32_e32 v18, v18
	s_nop 0
	v_mul_f32_e32 v17, v17, v18
	v_mul_f32_e32 v21, v16, v17
	v_pk_mul_f32 v[16:17], v[22:23], v[166:167] op_sel_hi:[1,0]
	s_nop 0
	v_mul_f32_e32 v18, 0xbfb8aa3b, v17
	v_exp_f32_e32 v18, v18
	s_nop 0
	v_add_f32_e32 v18, 1.0, v18
	v_rcp_f32_e32 v18, v18
	s_nop 0
	v_mul_f32_e32 v17, v17, v18
	v_mul_f32_e32 v19, v16, v17
	v_cvt_pk_bf16_f32 v18, v24, v20
	v_cvt_pk_bf16_f32 v19, v21, v19
	v_mad_i64_i32 v[20:21], s[10:11], v33, s47, v[112:113]
	v_lshl_add_u64 v[20:21], v[20:21], 0, v[114:115]
	v_cvt_pk_bf16_f32 v16, v34, v28
	v_cvt_pk_bf16_f32 v17, v26, v27
	flat_store_dwordx4 v[20:21], v[16:19]
	s_nop 0
	s_nop 0
	v_add_u32_e32 v17, 0xb0, v138
	v_mov_b32_e32 v18, v8
	v_mov_b32_e32 v19, v12
	v_mov_b32_e32 v12, v9
	s_nop 0
	v_pk_mul_f32 v[18:19], v[18:19], v[168:169] op_sel_hi:[1,0]
	s_nop 0
	v_mul_f32_e32 v8, 0xbfb8aa3b, v19
	v_exp_f32_e32 v8, v8
	s_nop 0
	v_add_f32_e32 v8, 1.0, v8
	v_rcp_f32_e32 v8, v8
	s_nop 0
	v_mul_f32_e32 v8, v19, v8
	v_mul_f32_e32 v18, v18, v8
	v_pk_mul_f32 v[8:9], v[12:13], v[168:169] op_sel_hi:[1,0]
	s_nop 0
	v_mul_f32_e32 v12, 0xbfb8aa3b, v9
	v_exp_f32_e32 v12, v12
	s_nop 0
	v_add_f32_e32 v12, 1.0, v12
	v_rcp_f32_e32 v12, v12
	s_nop 0
	v_mul_f32_e32 v9, v9, v12
	v_mul_f32_e32 v12, v8, v9
	v_mov_b32_e32 v8, v10
	v_mov_b32_e32 v9, v14
	v_pk_mul_f32 v[8:9], v[8:9], v[168:169] op_sel_hi:[1,0]
	v_mov_b32_e32 v14, v11
	v_mul_f32_e32 v10, 0xbfb8aa3b, v9
	v_exp_f32_e32 v10, v10
	s_nop 0
	v_add_f32_e32 v10, 1.0, v10
	v_rcp_f32_e32 v10, v10
	s_nop 0
	v_mul_f32_e32 v9, v9, v10
	v_mul_f32_e32 v10, v8, v9
	v_pk_mul_f32 v[8:9], v[14:15], v[168:169] op_sel_hi:[1,0]
	s_nop 0
	v_mul_f32_e32 v11, 0xbfb8aa3b, v9
	v_exp_f32_e32 v11, v11
	s_nop 0
	v_add_f32_e32 v11, 1.0, v11
	v_rcp_f32_e32 v11, v11
	s_nop 0
	v_mul_f32_e32 v9, v9, v11
	v_mul_f32_e32 v11, v8, v9
	v_mov_b32_e32 v8, v0
	v_mov_b32_e32 v9, v4
	v_pk_mul_f32 v[8:9], v[8:9], v[168:169] op_sel_hi:[1,0]
	v_mov_b32_e32 v4, v1
	v_mul_f32_e32 v0, 0xbfb8aa3b, v9
	v_exp_f32_e32 v0, v0
	s_nop 0
	v_add_f32_e32 v0, 1.0, v0
	v_rcp_f32_e32 v0, v0
	s_nop 0
	v_mul_f32_e32 v0, v9, v0
	v_mul_f32_e32 v8, v8, v0
	v_pk_mul_f32 v[0:1], v[4:5], v[168:169] op_sel_hi:[1,0]
	s_nop 0
	v_mul_f32_e32 v4, 0xbfb8aa3b, v1
	v_exp_f32_e32 v4, v4
	s_nop 0
	v_add_f32_e32 v4, 1.0, v4
	v_rcp_f32_e32 v4, v4
	s_nop 0
	v_mul_f32_e32 v1, v1, v4
	v_mul_f32_e32 v4, v0, v1
	v_mov_b32_e32 v0, v2
	v_mov_b32_e32 v1, v6
	v_pk_mul_f32 v[0:1], v[0:1], v[168:169] op_sel_hi:[1,0]
	v_mov_b32_e32 v6, v3
	v_mul_f32_e32 v2, 0xbfb8aa3b, v1
	v_exp_f32_e32 v2, v2
	s_nop 0
	v_add_f32_e32 v2, 1.0, v2
	v_rcp_f32_e32 v2, v2
	s_nop 0
	v_mul_f32_e32 v1, v1, v2
	v_mul_f32_e32 v5, v0, v1
	v_pk_mul_f32 v[0:1], v[6:7], v[168:169] op_sel_hi:[1,0]
	s_nop 0
	v_mul_f32_e32 v2, 0xbfb8aa3b, v1
	v_exp_f32_e32 v2, v2
	s_nop 0
	v_add_f32_e32 v2, 1.0, v2
	v_rcp_f32_e32 v2, v2
	s_nop 0
	v_mul_f32_e32 v1, v1, v2
	v_mul_f32_e32 v3, v0, v1
	v_cvt_pk_bf16_f32 v2, v8, v4
	v_cvt_pk_bf16_f32 v3, v5, v3
	v_mad_i64_i32 v[4:5], s[10:11], v17, s47, v[112:113]
	v_lshl_add_u64 v[4:5], v[4:5], 0, v[114:115]
	v_cvt_pk_bf16_f32 v0, v18, v12
	v_cvt_pk_bf16_f32 v1, v10, v11
	flat_store_dwordx4 v[4:5], v[0:3]
	s_cbranch_vccnz .LBB0_540
	s_andn2_b64 vcc, exec, s[0:1]
	s_cbranch_vccnz .LBB0_539
	s_barrier
	s_branch .LBB0_539
